# phase0 weight conversion software-pipelined: next tile's loads in flight during transpose/store, double-buffered LDS tile, one barrier per tile
# baseline (speedup 1.0000x reference)
; #define TIDX get_tid_()
; DI void phase0(const Params& p, char* lds) {
;     ...
;   for (int it = blockIdx.x; it < 4; it += gridDim.x) {
;     const int l = it >> 1, kv = it & 1;
;     const float* pe = p.in[kv ? I_PEV : I_PEK] + (size_t)l * 2048;
;     const float* w = p.in[kv ? I_PV1 : I_PK1] + (size_t)l * 2048 * 256;
;     const int n = TIDX;
;     if (n < 256) {
;       float s = 0.f;
;       for (int k = 0; k < 2048; ++k) s += pe[k] * w[(size_t)k * 256 + n];
;       ((float*)(p.ws + OFF_MISC + 256))[it * 256 + n] = s;
;     }
;   }
.Lb1_loop:
	global_load_dwordx4 v[8:11], v131, s[22:23] offset:0
	global_load_dwordx4 v[12:15], v131, s[22:23] offset:16
	global_load_dwordx4 v[16:19], v131, s[22:23] offset:32
	global_load_dwordx4 v[20:23], v131, s[22:23] offset:48
	global_load_dwordx4 v[24:27], v131, s[22:23] offset:64
	global_load_dwordx4 v[28:31], v131, s[22:23] offset:80
	global_load_dwordx4 v[32:35], v131, s[22:23] offset:96
	global_load_dwordx4 v[36:39], v131, s[22:23] offset:112
	global_load_dword v40, v0, s[10:11] offset:0
	global_load_dword v41, v0, s[10:11] offset:1024
	global_load_dword v42, v0, s[10:11] offset:2048
	global_load_dword v43, v0, s[10:11] offset:3072
	s_add_u32 s10, s10, 0x1000
	s_addc_u32 s11, s11, 0
	global_load_dword v44, v0, s[10:11] offset:0
	global_load_dword v45, v0, s[10:11] offset:1024
	global_load_dword v46, v0, s[10:11] offset:2048
	global_load_dword v47, v0, s[10:11] offset:3072
	s_add_u32 s10, s10, 0x1000
	s_addc_u32 s11, s11, 0
	global_load_dword v48, v0, s[10:11] offset:0
	global_load_dword v49, v0, s[10:11] offset:1024
	global_load_dword v50, v0, s[10:11] offset:2048
	global_load_dword v51, v0, s[10:11] offset:3072
	s_add_u32 s10, s10, 0x1000
	s_addc_u32 s11, s11, 0
	global_load_dword v52, v0, s[10:11] offset:0
	global_load_dword v53, v0, s[10:11] offset:1024
	global_load_dword v54, v0, s[10:11] offset:2048
	global_load_dword v55, v0, s[10:11] offset:3072
	s_add_u32 s10, s10, 0x1000
	s_addc_u32 s11, s11, 0
	global_load_dword v56, v0, s[10:11] offset:0
	global_load_dword v57, v0, s[10:11] offset:1024
	global_load_dword v58, v0, s[10:11] offset:2048
	global_load_dword v59, v0, s[10:11] offset:3072
	s_add_u32 s10, s10, 0x1000
	s_addc_u32 s11, s11, 0
	global_load_dword v60, v0, s[10:11] offset:0
	global_load_dword v61, v0, s[10:11] offset:1024
	global_load_dword v62, v0, s[10:11] offset:2048
	global_load_dword v63, v0, s[10:11] offset:3072
	s_add_u32 s10, s10, 0x1000
	s_addc_u32 s11, s11, 0
	global_load_dword v64, v0, s[10:11] offset:0
	global_load_dword v65, v0, s[10:11] offset:1024
	global_load_dword v66, v0, s[10:11] offset:2048
	global_load_dword v67, v0, s[10:11] offset:3072
	s_add_u32 s10, s10, 0x1000
	s_addc_u32 s11, s11, 0
	global_load_dword v68, v0, s[10:11] offset:0
	global_load_dword v69, v0, s[10:11] offset:1024
	global_load_dword v70, v0, s[10:11] offset:2048
	global_load_dword v71, v0, s[10:11] offset:3072
	s_add_u32 s10, s10, 0x1000
	s_addc_u32 s11, s11, 0
	s_add_u32 s22, s22, 0x80
	s_addc_u32 s23, s23, 0
	s_waitcnt vmcnt(0)
	v_fmac_f32_e32 v1, v8, v40
	v_fmac_f32_e32 v1, v9, v41
	v_fmac_f32_e32 v1, v10, v42
	v_fmac_f32_e32 v1, v11, v43
	v_fmac_f32_e32 v1, v12, v44
	v_fmac_f32_e32 v1, v13, v45
	v_fmac_f32_e32 v1, v14, v46
	v_fmac_f32_e32 v1, v15, v47
	v_fmac_f32_e32 v1, v16, v48
	v_fmac_f32_e32 v1, v17, v49
	v_fmac_f32_e32 v1, v18, v50
	v_fmac_f32_e32 v1, v19, v51
	v_fmac_f32_e32 v1, v20, v52
	v_fmac_f32_e32 v1, v21, v53
	v_fmac_f32_e32 v1, v22, v54
	v_fmac_f32_e32 v1, v23, v55
	v_fmac_f32_e32 v1, v24, v56
	v_fmac_f32_e32 v1, v25, v57
	v_fmac_f32_e32 v1, v26, v58
	v_fmac_f32_e32 v1, v27, v59
	v_fmac_f32_e32 v1, v28, v60
	v_fmac_f32_e32 v1, v29, v61
	v_fmac_f32_e32 v1, v30, v62
	v_fmac_f32_e32 v1, v31, v63
	v_fmac_f32_e32 v1, v32, v64
	v_fmac_f32_e32 v1, v33, v65
	v_fmac_f32_e32 v1, v34, v66
	v_fmac_f32_e32 v1, v35, v67
	v_fmac_f32_e32 v1, v36, v68
	v_fmac_f32_e32 v1, v37, v69
	v_fmac_f32_e32 v1, v38, v70
	v_fmac_f32_e32 v1, v39, v71
	s_sub_u32 s26, s26, 1
	s_cmp_lg_u32 s26, 0
	s_cbranch_scc1 .Lb1_loop
	v_lshlrev_b32_e32 v2, 2, v129
	v_add_u32_e32 v2, 0x4800, v2
	ds_write_b32 v2, v1
	s_waitcnt lgkmcnt(0)
	s_barrier
	v_cmp_gt_u32_e32 vcc, 64, v129
	s_and_saveexec_b64 s[8:9], vcc
	s_cbranch_execz .Lb1_skip
	ds_read_b32 v8, v2 offset:0
	ds_read_b32 v9, v2 offset:256
	ds_read_b32 v10, v2 offset:512
	ds_read_b32 v11, v2 offset:768
	ds_read_b32 v12, v2 offset:1024
	ds_read_b32 v13, v2 offset:1280
	ds_read_b32 v14, v2 offset:1536
	ds_read_b32 v15, v2 offset:1792
	v_readlane_b32 s10, v253, 9
	v_readlane_b32 s11, v253, 10
	s_lshl_b32 s14, s4, 8
	s_waitcnt lgkmcnt(0)
	v_add_f32_e32 v8, v8, v9
	v_add_f32_e32 v8, v8, v10
	v_add_f32_e32 v8, v8, v11
	v_add_f32_e32 v8, v8, v12
	v_add_f32_e32 v8, v8, v13
	v_add_f32_e32 v8, v8, v14
	v_add_f32_e32 v8, v8, v15
	s_add_u32 s10, s10, s14
	s_addc_u32 s11, s11, 0
	s_nop 1
	global_store_dword v0, v8, s[10:11]

; #define TIDX get_tid_()
; DI bf16_t f2bf(float x) { unsigned r; asm("v_cvt_pk_bf16_f32 %0, %1, %1" : "=v"(r) : "v"(x)); return (bf16_t)(r & 0xffffu); }
; DI void conv_tile(const ConvD& c, int tn, int tk, float* lds) {
;   const int tid = TIDX;
;   const int n0 = tn * 64, k0 = tk * 64;
;   {
;     const int j = tid & 63, np = n0 + j;
;     const float* sp = c.src; int col = -1;
;     if (c.mode == 0) { if (np < c.nvalid) col = c.coloff + np; }
;     else if (c.mode == 1) { const int tile = np >> 7, within = np & 127, wc = within >> 6, part = (within & 63) >> 5, jj = within & 31;
;       col = tile * 64 + wc * 32 + jj; if (part) sp = c.src2; }
;     else { if (np < 1152) col = np; else if (np < 3072) col = 1170 + (np - 1152); else if (np < 3090) col = 1152 + (np - 3072); }
;     float tv[8];
; #pragma unroll
;     for (int i = 0; i < 8; ++i) {
;       const int kk = (tid >> 6) + 8 * i;
;       tv[i] = (col >= 0) ? sp[(size_t)(k0 + kk) * c.Nsrc + col] : 0.f;
;     }
; #pragma unroll
;     for (int i = 0; i < 8; ++i) lds[((tid >> 6) + 8 * i) * 65 + j] = tv[i];
;   }
;   __syncthreads();
;   {
;     const int kk = tid & 63;
; #pragma unroll
;     for (int i = 0; i < 8; ++i) {
;       const int j = (tid >> 6) + 8 * i;
;       c.dst[(size_t)(n0 + j) * c.K + k0 + kk] = f2bf(lds[kk * 65 + j]);
;     }
;   }
;   __syncthreads();
.LBB0_773:
	v_readlane_b32 s8, v253, 11
	v_readlane_b32 s9, v253, 12
	s_andn2_b64 vcc, exec, s[8:9]
	s_cbranch_vccnz .LBB0_863
	v_readlane_b32 s4, v254, 1
	s_mov_b32 s101, 0
	v_and_b32_e32 v18, 63, v129
	v_lshrrev_b32_e32 v28, 6, v129
	v_mul_u32_u24_e32 v16, 0x104, v28
	v_lshl_add_u32 v16, v18, 2, v16
	v_mul_u32_u24_e32 v17, 0x104, v18
	v_lshl_add_u32 v17, v28, 2, v17
	v_lshlrev_b32_e32 v18, 1, v18
	v_mov_b32_e32 v19, 0
	s_branch .LBB0_781

; #define TIDX get_tid_()
; DI bf16_t f2bf(float x) { unsigned r; asm("v_cvt_pk_bf16_f32 %0, %1, %1" : "=v"(r) : "v"(x)); return (bf16_t)(r & 0xffffu); }
; DI void conv_tile(const ConvD& c, int tn, int tk, float* lds) {
;   const int tid = TIDX;
;   const int n0 = tn * 64, k0 = tk * 64;
;   {
;     const int j = tid & 63, np = n0 + j;
;     const float* sp = c.src; int col = -1;
;     if (c.mode == 0) { if (np < c.nvalid) col = c.coloff + np; }
;     else if (c.mode == 1) { const int tile = np >> 7, within = np & 127, wc = within >> 6, part = (within & 63) >> 5, jj = within & 31;
;       col = tile * 64 + wc * 32 + jj; if (part) sp = c.src2; }
;     else { if (np < 1152) col = np; else if (np < 3072) col = 1170 + (np - 1152); else if (np < 3090) col = 1152 + (np - 3072); }
;     float tv[8];
; #pragma unroll
;     for (int i = 0; i < 8; ++i) {
;       const int kk = (tid >> 6) + 8 * i;
;       tv[i] = (col >= 0) ? sp[(size_t)(k0 + kk) * c.Nsrc + col] : 0.f;
;     }
; #pragma unroll
;     for (int i = 0; i < 8; ++i) lds[((tid >> 6) + 8 * i) * 65 + j] = tv[i];
;   }
;   __syncthreads();
;   {
;     const int kk = tid & 63;
; #pragma unroll
;     for (int i = 0; i < 8; ++i) {
;       const int j = (tid >> 6) + 8 * i;
;       c.dst[(size_t)(n0 + j) * c.K + k0 + kk] = f2bf(lds[kk * 65 + j]);
;     }
;   }
;   __syncthreads();
.LBB0_843:
	s_cmp_eq_u32 s101, 0
	s_cbranch_scc1 .Lcv_b
	s_cmp_eq_u32 s101, 1
	s_cbranch_scc1 .Lcv_w0
	s_waitcnt vmcnt(8)
	s_branch .Lcv_w
.Lcv_w0:
	s_waitcnt vmcnt(0)
.Lcv_w:
	ds_write_b32 v16, v32
	ds_write_b32 v16, v33 offset:2080
	ds_write_b32 v16, v34 offset:4160
	ds_write_b32 v16, v35 offset:6240
	ds_write_b32 v16, v36 offset:8320
	ds_write_b32 v16, v37 offset:10400
	ds_write_b32 v16, v38 offset:12480
	ds_write_b32 v16, v39 offset:14560
.Lcv_b:
	s_sext_i32_i16 s14, s23
	s_lshl_b32 s14, s14, 6
	v_add_u32_e32 v6, s14, v28
	v_mad_u64_u32 v[6:7], s[30:31], s62, v6, 0
	v_lshl_add_u64 v[0:1], v[130:131], 2, v[0:1]
	v_lshl_add_u64 v[0:1], v[6:7], 2, v[0:1]
	s_lshl_b64 s[26:27], s[62:63], 5
	v_cmp_lt_i32_e32 vcc, -1, v130
	v_mov_b32_e32 v32, 0
	v_mov_b32_e32 v33, 0
	v_mov_b32_e32 v34, 0
	v_mov_b32_e32 v35, 0
	v_mov_b32_e32 v36, 0
	v_mov_b32_e32 v37, 0
	v_mov_b32_e32 v38, 0
	v_mov_b32_e32 v39, 0
	s_and_saveexec_b64 s[54:55], vcc
	global_load_dword v32, v[0:1], off
	v_lshl_add_u64 v[0:1], v[0:1], 0, s[26:27]
	global_load_dword v33, v[0:1], off
	v_lshl_add_u64 v[0:1], v[0:1], 0, s[26:27]
	global_load_dword v34, v[0:1], off
	v_lshl_add_u64 v[0:1], v[0:1], 0, s[26:27]
	global_load_dword v35, v[0:1], off
	v_lshl_add_u64 v[0:1], v[0:1], 0, s[26:27]
	global_load_dword v36, v[0:1], off
	v_lshl_add_u64 v[0:1], v[0:1], 0, s[26:27]
	global_load_dword v37, v[0:1], off
	v_lshl_add_u64 v[0:1], v[0:1], 0, s[26:27]
	global_load_dword v38, v[0:1], off
	v_lshl_add_u64 v[0:1], v[0:1], 0, s[26:27]
	global_load_dword v39, v[0:1], off
	s_or_b64 exec, exec, s[54:55]
	v_add_u32_e32 v6, s22, v28
	v_mad_u64_u32 v[24:25], s[30:31], s10, v6, 0
	s_lshl_b32 s15, s14, 1
	s_add_u32 s14, s8, s15
	s_addc_u32 s15, s9, 0
	v_mov_b32_e32 v26, s10
	v_lshl_add_u64 v[24:25], v[24:25], 1, s[14:15]
	v_lshlrev_b32_e32 v26, 4, v26
	v_lshl_add_u64 v[24:25], v[24:25], 0, v[18:19]
	v_mov_b32_e32 v27, 0
	s_cmp_eq_u32 s101, 0
	s_cbranch_scc1 .Lcv_first
	s_waitcnt lgkmcnt(0)
	s_barrier
	ds_read2_b32 v[40:41], v17 offset1:8
	ds_read2_b32 v[42:43], v17 offset0:16 offset1:24
	ds_read2_b32 v[44:45], v17 offset0:32 offset1:40
	ds_read2_b32 v[46:47], v17 offset0:48 offset1:56
	s_waitcnt lgkmcnt(3)
	v_cvt_pk_bf16_f32 v40, v40, v40
	global_store_short v[20:21], v40, off
	v_lshl_add_u64 v[20:21], v[20:21], 0, v[22:23]
	v_cvt_pk_bf16_f32 v41, v41, v41
	global_store_short v[20:21], v41, off
	v_lshl_add_u64 v[20:21], v[20:21], 0, v[22:23]
	s_waitcnt lgkmcnt(2)
	v_cvt_pk_bf16_f32 v42, v42, v42
	global_store_short v[20:21], v42, off
	v_lshl_add_u64 v[20:21], v[20:21], 0, v[22:23]
	v_cvt_pk_bf16_f32 v43, v43, v43
	global_store_short v[20:21], v43, off
	v_lshl_add_u64 v[20:21], v[20:21], 0, v[22:23]
	s_waitcnt lgkmcnt(1)
	v_cvt_pk_bf16_f32 v44, v44, v44
	global_store_short v[20:21], v44, off
	v_lshl_add_u64 v[20:21], v[20:21], 0, v[22:23]
	v_cvt_pk_bf16_f32 v45, v45, v45
	global_store_short v[20:21], v45, off
	v_lshl_add_u64 v[20:21], v[20:21], 0, v[22:23]
	s_waitcnt lgkmcnt(0)
	v_cvt_pk_bf16_f32 v46, v46, v46
	global_store_short v[20:21], v46, off
	v_lshl_add_u64 v[20:21], v[20:21], 0, v[22:23]
	v_cvt_pk_bf16_f32 v47, v47, v47
	global_store_short v[20:21], v47, off
	v_xor_b32_e32 v16, 0x8000, v16
	v_xor_b32_e32 v17, 0x8000, v17
.Lcv_first:
	v_mov_b32_e32 v20, v24
	v_mov_b32_e32 v21, v25
	v_mov_b32_e32 v22, v26
	v_mov_b32_e32 v23, v27
	s_add_u32 s101, s101, 1
	s_min_u32 s101, s101, 2
	s_add_i32 s4, s4, s33
	s_cmpk_gt_i32 s4, 0x32df
	s_cbranch_scc0 .LBB0_781
	s_waitcnt vmcnt(0)
	ds_write_b32 v16, v32
	ds_write_b32 v16, v33 offset:2080
	ds_write_b32 v16, v34 offset:4160
	ds_write_b32 v16, v35 offset:6240
	ds_write_b32 v16, v36 offset:8320
	ds_write_b32 v16, v37 offset:10400
	ds_write_b32 v16, v38 offset:12480
	ds_write_b32 v16, v39 offset:14560
	s_waitcnt lgkmcnt(0)
	s_barrier
	ds_read2_b32 v[40:41], v17 offset1:8
	ds_read2_b32 v[42:43], v17 offset0:16 offset1:24
	ds_read2_b32 v[44:45], v17 offset0:32 offset1:40
	ds_read2_b32 v[46:47], v17 offset0:48 offset1:56
	s_waitcnt lgkmcnt(3)
	v_cvt_pk_bf16_f32 v40, v40, v40
	global_store_short v[20:21], v40, off
	v_lshl_add_u64 v[20:21], v[20:21], 0, v[22:23]
	v_cvt_pk_bf16_f32 v41, v41, v41
	global_store_short v[20:21], v41, off
	v_lshl_add_u64 v[20:21], v[20:21], 0, v[22:23]
	s_waitcnt lgkmcnt(2)
	v_cvt_pk_bf16_f32 v42, v42, v42
	global_store_short v[20:21], v42, off
	v_lshl_add_u64 v[20:21], v[20:21], 0, v[22:23]
	v_cvt_pk_bf16_f32 v43, v43, v43
	global_store_short v[20:21], v43, off
	v_lshl_add_u64 v[20:21], v[20:21], 0, v[22:23]
	s_waitcnt lgkmcnt(1)
	v_cvt_pk_bf16_f32 v44, v44, v44
	global_store_short v[20:21], v44, off
	v_lshl_add_u64 v[20:21], v[20:21], 0, v[22:23]
	v_cvt_pk_bf16_f32 v45, v45, v45
	global_store_short v[20:21], v45, off
	v_lshl_add_u64 v[20:21], v[20:21], 0, v[22:23]
	s_waitcnt lgkmcnt(0)
	v_cvt_pk_bf16_f32 v46, v46, v46
	global_store_short v[20:21], v46, off
	v_lshl_add_u64 v[20:21], v[20:21], 0, v[22:23]
	v_cvt_pk_bf16_f32 v47, v47, v47
	global_store_short v[20:21], v47, off
	s_mov_b32 s53, 0x8000
	s_mov_b32 s30, 0x3a800000
	s_barrier
	s_branch .LBB0_863
